# retout unit: K/V chunk loads issued together; gate/gain epilogue loads hoisted to the q-load point (no serialized load-wait-store blocks)
# speedup vs baseline: 1.0377x; 1.0029x over previous
; #define LAS __attribute__((address_space(3)))
; __device__ __forceinline__ void retout_unit(CArgs& a, int l, unsigned char* lds, int u, const int tid) {
;     unsigned char* ws = a.ws;
;     const int b = u >> 7, h = (u >> 5) & 3, n = u & 31;
;     const int lane = tid & 63, w = __builtin_amdgcn_readfirstlane(tid >> 6), fr = lane & 15, fq = lane >> 4;
;     const bf16_t* RQ = (const bf16_t*)(ws + WS_R + R_RQ); const bf16_t* RK = (const bf16_t*)(ws + WS_R + R_RK); const bf16_t* RV = (const bf16_t*)(ws + WS_R + R_RV);
;     const bf16_t* RG = (const bf16_t*)(ws + WS_R + R_RG); const bf16_t* KV = (const bf16_t*)(ws + WS_KV);
;     bf16_t* OC = (bf16_t*)(ws + WS_R + R_OCAT);
;     const float lg2 = log2f(1.f - exp2f(-5.f - (float)h));
;     const size_t row0 = (size_t)b * SEQ + n * 128;
;     LAS bf16_t* KS = (LAS bf16_t*)lds; LAS bf16_t* VT = KS + 128 * RP64; LAS bf16_t* RT = VT + 64 * RP128; LAS bf16_t* PS = RT + 64 * RP64;
;     __syncthreads();
;     { const int r = tid >> 2, c0 = (tid & 3) * 16;
;       const u32x4* ksrc = (const u32x4*)(RK + (row0 + r) * 256 + h * 64 + c0); const u32x4 k0 = ksrc[0], k1 = ksrc[1];
;       *(LAS u32x4*)(KS + r * RP64 + c0) = k0; *(LAS u32x4*)(KS + r * RP64 + c0 + 8) = k1;
;       const u32x4* vs = (const u32x4*)(RV + (row0 + r) * 256 + h * 64 + c0); const u32x4 a0 = vs[0], a1 = vs[1];
;       const unsigned vw[8] = {a0.x, a0.y, a0.z, a0.w, a1.x, a1.y, a1.z, a1.w};
; #pragma unroll
;       for (int i = 0; i < 8; ++i) { VT[(c0 + 2 * i) * RP128 + r] = (bf16_t)(vw[i] & 0xffffu); VT[(c0 + 2 * i + 1) * RP128 + r] = (bf16_t)(vw[i] >> 16); } }
.LBB0_126:
	s_bfe_u32 s44, s42, 0x20005
	v_cvt_f32_ubyte0_e32 v0, s44
	v_sub_f32_e32 v0, 0xc0a00000, v0
	v_cmp_gt_f32_e32 vcc, s87, v0
	s_lshr_b32 s63, s42, 5
	s_and_b32 s65, s63, 24
	v_cndmask_b32_e32 v2, 0, v189, vcc
	v_add_f32_e32 v0, v0, v2
	s_add_i32 s6, s65, s42
	v_exp_f32_e32 v0, v0
	s_and_b32 s45, s6, 31
	s_ashr_i32 s58, s42, 7
	s_and_b64 s[6:7], vcc, exec
	s_cselect_b32 s6, 0xffffffc0, 0
	s_ashr_i32 s59, s58, 31
	v_ldexp_f32 v0, v0, s6
	s_lshl_b64 s[56:57], s[58:59], 12
	s_lshl_b32 s6, s45, 7
	s_or_b32 s6, s56, s6
	s_mov_b32 s7, s57
	v_lshl_add_u64 v[4:5], s[6:7], 0, v[68:69]
	v_lshlrev_b64 v[12:13], 9, v[4:5]
	v_lshl_add_u64 v[4:5], s[14:15], 0, v[12:13]
	s_lshl_b32 s28, s44, 7
	v_lshl_add_u64 v[4:5], v[4:5], 0, s[28:29]
	v_mov_b32_e32 v91, v1
	v_lshl_add_u64 v[8:9], v[4:5], 0, v[90:91]
	s_waitcnt vmcnt(0)
	s_barrier
	global_load_dwordx4 v[4:7], v[8:9], off offset:16
	s_nop 0
	global_load_dwordx4 v[8:11], v[8:9], off
	v_lshl_add_u64 v[242:243], s[48:49], 0, v[12:13]
	v_lshl_add_u64 v[242:243], v[242:243], 0, s[28:29]
	v_lshl_add_u64 v[242:243], v[242:243], 0, v[90:91]
	global_load_dwordx4 v[244:247], v[242:243], off
	global_load_dwordx4 v[248:251], v[242:243], off offset:16
	v_sub_f32_e32 v0, 1.0, v0
	v_cmp_gt_f32_e32 vcc, s74, v0
	s_and_b64 s[26:27], vcc, exec
	s_cselect_b32 s26, 32, 0
	v_ldexp_f32 v0, v0, s26
	v_log_f32_e32 v0, v0
	s_cmp_eq_u32 s45, 0
	v_cndmask_b32_e32 v2, 0, v190, vcc
	s_cselect_b64 s[60:61], -1, 0
	v_mov_b32_e32 v3, 0
	v_readfirstlane_b32 s43, v66
	s_and_b64 vcc, exec, s[60:61]
	s_waitcnt vmcnt(2)
	ds_write_b128 v96, v[8:11]
	ds_write_b128 v96, v[4:7] offset:16
	v_sub_f32_e32 v91, v0, v2
	v_mov_b32_e32 v2, 0
	s_waitcnt vmcnt(1)
	ds_write_b16 v97, v244 offset:18432
	ds_write_b16_d16_hi v97, v244 offset:18704
	ds_write_b16 v97, v245 offset:18976
	ds_write_b16_d16_hi v97, v245 offset:19248
	ds_write_b16 v97, v246 offset:19520
	ds_write_b16_d16_hi v97, v246 offset:19792
	ds_write_b16 v97, v247 offset:20064
	ds_write_b16_d16_hi v97, v247 offset:20336
	v_mov_b32_e32 v9, 0
	v_mov_b32_e32 v8, 0
	s_waitcnt vmcnt(0)
	ds_write_b16 v97, v248 offset:20608
	ds_write_b16_d16_hi v97, v248 offset:20880
	ds_write_b16 v97, v249 offset:21152
	ds_write_b16_d16_hi v97, v249 offset:21424
	ds_write_b16 v97, v250 offset:21696
	ds_write_b16_d16_hi v97, v250 offset:21968
	ds_write_b16 v97, v251 offset:22240
	ds_write_b16_d16_hi v97, v251 offset:22512
	v_mov_b32_e32 v5, 0
	v_mov_b32_e32 v4, 0
	v_mov_b32_e32 v7, 0
	v_mov_b32_e32 v6, 0
	s_cbranch_vccnz .LBB0_134
	s_mul_i32 s26, s19, s10
	s_add_i32 s26, s26, s11
	s_add_i32 s26, s26, s65
	s_and_b32 s64, s26, 31
	s_lshl_b32 s62, s63, 5
	v_mul_f32_e32 v12, 0x43000000, v91
	s_ashr_i32 s63, s62, 31
	s_lshl_b64 s[26:27], s[62:63], 13
	v_lshl_add_u64 v[10:11], v[70:71], 0, s[26:27]
	s_mov_b32 s65, 0
	s_add_i32 s59, s64, -1
	s_mov_b32 s63, 0

; #define LAS __attribute__((address_space(3)))
; __device__ __forceinline__ unsigned cvt_pk_bf16(float lo, float hi) { unsigned r; asm volatile("v_cvt_pk_bf16_f32 %0, %1, %2" : "=v"(r) : "v"(lo), "v"(hi)); return r; }
; __device__ __forceinline__ void retout_unit(CArgs& a, int l, unsigned char* lds, int u, const int tid) {
;     ...
;       u32x4 o; o.x = cvt_pk_bf16(r[0], r[1]); o.y = cvt_pk_bf16(r[2], r[3]); o.z = cvt_pk_bf16(r[4], r[5]); o.w = cvt_pk_bf16(r[6], r[7]);
;       *(LAS u32x4*)(RT + (tid >> 3) * RP64 + (tid & 7) * 8) = o; }
;     const int c = 16 * w + fr; const size_t row = row0 + c;
;     const bf16x8 qf0 = *(const bf16x8*)(RQ + row * 256 + h * 64 + 8 * fq), qf1 = *(const bf16x8*)(RQ + row * 256 + h * 64 + 32 + 8 * fq);
;     ...
;         const u32x2 gw = *(const u32x2*)(RG + row * 256 + h * 64 + e0); const f32x4 gg = *(const f32x4*)(a.in[I_RETG] + l * 64 + e0);
.LBB0_134:
	s_lshl_b32 s62, s43, 4
	v_or_b32_e32 v28, s62, v95
	v_ashrrev_i32_e32 v29, 31, v28
	v_lshl_add_u64 v[26:27], s[6:7], 0, v[28:29]
	s_lshl_b32 s44, s44, 6
	v_cvt_pk_bf16_f32 v10, v8, v9
	v_cvt_pk_bf16_f32 v11, v6, v7
	v_cvt_pk_bf16_f32 v12, v4, v5
	v_cvt_pk_bf16_f32 v13, v2, v3
	v_lshlrev_b64 v[2:3], 9, v[26:27]
	v_lshl_add_u64 v[2:3], s[52:53], 0, v[2:3]
	s_lshl_b32 s28, s44, 1
	v_lshl_add_u64 v[2:3], v[2:3], 0, s[28:29]
	v_mov_b32_e32 v93, v1
	v_lshl_add_u64 v[6:7], v[2:3], 0, v[92:93]
	global_load_dwordx4 v[2:5], v[6:7], off
	s_nop 0
	global_load_dwordx4 v[6:9], v[6:7], off offset:64
	v_lshlrev_b64 v[244:245], 8, v[26:27]
	v_lshlrev_b32_e32 v246, 1, v74
	v_mov_b32_e32 v247, 0
	v_lshl_add_u64 v[244:245], v[244:245], 1, s[50:51]
	v_lshl_add_u64 v[244:245], v[244:245], 0, s[28:29]
	v_lshl_add_u64 v[244:245], v[244:245], 0, v[246:247]
	global_load_dwordx2 v[208:209], v[244:245], off
	global_load_dwordx4 v[216:219], v[76:77], off
	global_load_dwordx2 v[210:211], v[244:245], off offset:32
	global_load_dwordx4 v[220:223], v[76:77], off offset:64
	global_load_dwordx2 v[212:213], v[244:245], off offset:64
	global_load_dwordx4 v[224:227], v[76:77], off offset:128
	global_load_dwordx2 v[214:215], v[244:245], off offset:96
	global_load_dwordx4 v[228:231], v[76:77], off offset:192
	s_cmp_lt_i32 s43, 0
	s_mul_i32 s45, s43, 0x1100
	ds_write_b128 v107, v[10:13] offset:35840
	s_waitcnt lgkmcnt(0)
	s_barrier
	s_cbranch_scc1 .LBB0_137
	s_add_i32 s59, s43, 1
	v_add_u32_e32 v0, s45, v111
	v_add_u32_e32 v10, s62, v112
	v_mov_b32_e32 v11, v98

; #define LAS __attribute__((address_space(3)))
; __device__ __forceinline__ unsigned cvt_pk_bf16(float lo, float hi) { unsigned r; asm volatile("v_cvt_pk_bf16_f32 %0, %1, %2" : "=v"(r) : "v"(lo), "v"(hi)); return r; }
; __device__ __forceinline__ float bflo(unsigned w) { return __uint_as_float(w << 16); }
; __device__ __forceinline__ float bfhi(unsigned w) { return __uint_as_float(w & 0xffff0000u); }
; __device__ __forceinline__ void retout_unit(CArgs& a, int l, unsigned char* lds, int u, const int tid) {
;     ...
;     for (int et = 0; et < 4; ++et) { const bf16x8 r0 = *(const LAS bf16x8*)(RT + (16 * et + fr) * RP64 + 8 * fq), r1 = *(const LAS bf16x8*)(RT + (16 * et + fr) * RP64 + 32 + 8 * fq);
;         x[et] = __builtin_amdgcn_mfma_f32_16x16x32_bf16(r0, qf0, x[et], 0, 0, 0); x[et] = __builtin_amdgcn_mfma_f32_16x16x32_bf16(r1, qf1, x[et], 0, 0, 0); }
;     const float qd = exp2f(lg2 * (float)(c + 1));
;     float ss = 0.f;
; #pragma unroll
;     for (int et = 0; et < 4; ++et) { o[et] += x[et] * qd; ss += (o[et][0] * o[et][0] + o[et][1] * o[et][1]) + (o[et][2] * o[et][2] + o[et][3] * o[et][3]); }
;     ss += __shfl_xor(ss, 16); ss += __shfl_xor(ss, 32);
;     const float ri = rsqrtf(ss * (1.f / 64.f) + EPS);
;     const bool head_rows = (n == 0 && c < 8);
; #pragma unroll
;     for (int et = 0; et < 4; ++et) { const int e0 = 16 * et + 4 * fq;
;         const u32x2 gw = *(const u32x2*)(RG + row * 256 + h * 64 + e0); const f32x4 gg = *(const f32x4*)(a.in[I_RETG] + l * 64 + e0);
;         u32x2 ow; ow.x = cvt_pk_bf16(o[et][0] * ri * gg[0] * bflo(gw.x), o[et][1] * ri * gg[1] * bfhi(gw.x)); ow.y = cvt_pk_bf16(o[et][2] * ri * gg[2] * bflo(gw.y), o[et][3] * ri * gg[3] * bfhi(gw.y));
;         if (!head_rows) *(u32x2*)(OC + row * 1024 + 512 + h * 64 + e0) = ow; }
.LBB0_142:
	ds_read_b128 v[32:35], v98 offset:35840
	ds_read_b128 v[36:39], v98 offset:35904
	v_add_u32_e32 v0, 1, v28
	v_cvt_f32_i32_e32 v0, v0
	v_lshlrev_b64 v[30:31], 8, v[26:27]
	s_waitcnt vmcnt(1) lgkmcnt(1)
	v_mfma_f32_16x16x32_bf16 v[32:35], v[32:35], v[2:5], 0
	s_xor_b64 s[6:7], s[60:61], -1
	s_waitcnt vmcnt(0) lgkmcnt(0)
	v_mfma_f32_16x16x32_bf16 v[32:35], v[36:39], v[6:9], v[32:35]
	ds_read_b128 v[36:39], v108 offset:35840
	ds_read_b128 v[40:43], v108 offset:35904
	s_waitcnt lgkmcnt(1)
	v_mfma_f32_16x16x32_bf16 v[36:39], v[36:39], v[2:5], 0
	s_waitcnt lgkmcnt(0)
	v_mfma_f32_16x16x32_bf16 v[36:39], v[40:43], v[6:9], v[36:39]
	ds_read_b128 v[40:43], v109 offset:35840
	ds_read_b128 v[44:47], v109 offset:35904
	s_waitcnt lgkmcnt(1)
	v_mfma_f32_16x16x32_bf16 v[40:43], v[40:43], v[2:5], 0
	s_waitcnt lgkmcnt(0)
	v_mfma_f32_16x16x32_bf16 v[40:43], v[44:47], v[6:9], v[40:43]
	ds_read_b128 v[44:47], v110 offset:35840
	ds_read_b128 v[48:51], v110 offset:35904
	s_waitcnt lgkmcnt(1)
	v_mfma_f32_16x16x32_bf16 v[2:5], v[44:47], v[2:5], 0
	s_waitcnt lgkmcnt(0)
	v_mfma_f32_16x16x32_bf16 v[2:5], v[48:51], v[6:9], v[2:5]
	v_mul_f32_e32 v6, v91, v0
	v_cmp_gt_f32_e32 vcc, s87, v6
	s_nop 1
	v_cndmask_b32_e32 v6, 0, v189, vcc
	v_fmac_f32_e32 v6, v91, v0
	v_exp_f32_e32 v0, v6
	v_cndmask_b32_e32 v6, 0, v191, vcc
	v_ldexp_f32 v0, v0, v6
	v_pk_fma_f32 v[24:25], v[0:1], v[34:35], v[24:25] op_sel_hi:[0,1,1]
	v_pk_fma_f32 v[22:23], v[0:1], v[32:33], v[22:23] op_sel_hi:[0,1,1]
	v_pk_mul_f32 v[6:7], v[24:25], v[24:25]
	v_pk_mul_f32 v[8:9], v[22:23], v[22:23]
	v_pk_fma_f32 v[20:21], v[0:1], v[38:39], v[20:21] op_sel_hi:[0,1,1]
	v_pk_mov_b32 v[32:33], v[8:9], v[6:7] op_sel:[1,0]
	v_mov_b32_e32 v9, v7
	v_pk_fma_f32 v[18:19], v[0:1], v[36:37], v[18:19] op_sel_hi:[0,1,1]
	v_pk_add_f32 v[32:33], v[32:33], v[8:9]
	v_pk_mul_f32 v[6:7], v[20:21], v[20:21]
	v_pk_mul_f32 v[8:9], v[18:19], v[18:19]
	v_pk_fma_f32 v[16:17], v[0:1], v[42:43], v[16:17] op_sel_hi:[0,1,1]
	v_pk_mov_b32 v[34:35], v[8:9], v[6:7] op_sel:[1,0]
	v_mov_b32_e32 v9, v7
	v_pk_add_f32 v[34:35], v[34:35], v[8:9]
	v_pk_fma_f32 v[8:9], v[0:1], v[2:3], v[10:11] op_sel_hi:[0,1,1]
	v_pk_fma_f32 v[14:15], v[0:1], v[40:41], v[14:15] op_sel_hi:[0,1,1]
	v_pk_fma_f32 v[6:7], v[0:1], v[4:5], v[12:13] op_sel_hi:[0,1,1]
	v_mul_f32_e32 v0, v8, v8
	v_mul_f32_e32 v10, v9, v9
	v_pk_add_f32 v[2:3], v[32:33], v[32:33] op_sel:[0,1] op_sel_hi:[1,0]
	v_pk_add_f32 v[4:5], v[34:35], v[34:35] op_sel:[0,1] op_sel_hi:[1,0]
	v_mov_b32_e32 v3, v0
	v_mov_b32_e32 v5, v10
	v_mul_f32_e32 v0, v15, v15
	v_mul_f32_e32 v11, v6, v6
	v_pk_add_f32 v[2:3], v[2:3], v[4:5]
	v_pk_fma_f32 v[4:5], v[14:15], v[14:15], v[0:1] op_sel_hi:[1,1,0]
	v_mul_f32_e32 v0, v17, v17
	v_mul_f32_e32 v12, v7, v7
	v_mov_b32_e32 v5, v11
	v_pk_fma_f32 v[10:11], v[16:17], v[16:17], v[0:1] op_sel_hi:[1,1,0]
	s_nop 0
	v_mov_b32_e32 v11, v12
	v_pk_add_f32 v[4:5], v[4:5], v[10:11]
	s_nop 0
	v_pk_add_f32 v[2:3], v[2:3], v[4:5]
	v_lshlrev_b64 v[4:5], 11, v[26:27]
	v_add_f32_e32 v0, v2, v3
	v_and_b32_e32 v3, 64, v187
	v_xor_b32_e32 v2, 16, v187
	v_add_u32_e32 v115, 64, v3
	v_cmp_lt_i32_e32 vcc, v2, v115
	v_lshl_add_u64 v[4:5], s[12:13], 0, v[4:5]
	v_lshl_add_u64 v[10:11], v[4:5], 0, s[28:29]
	v_cndmask_b32_e32 v2, v187, v2, vcc
	v_lshlrev_b32_e32 v93, 2, v2
	ds_bpermute_b32 v2, v93, v0
	s_waitcnt lgkmcnt(0)
	v_add_f32_e32 v0, v0, v2
	v_xor_b32_e32 v2, 32, v187
	v_cmp_lt_i32_e32 vcc, v2, v115
	s_nop 1
	v_cndmask_b32_e32 v2, v187, v2, vcc
	v_lshlrev_b32_e32 v116, 2, v2
	ds_bpermute_b32 v2, v116, v0
	s_waitcnt lgkmcnt(0)
	v_add_f32_e32 v0, v0, v2
	v_fmamk_f32 v0, v0, 0x3c800000, v184
	v_cmp_gt_f32_e32 vcc, s74, v0
	v_mul_f32_e32 v2, 0x4b800000, v0
	s_nop 0
	v_cndmask_b32_e32 v0, v0, v2, vcc
	v_rsq_f32_e32 v0, v0
	s_nop 0
	v_mul_f32_e32 v2, 0x45800000, v0
	v_cndmask_b32_e32 v29, v0, v2, vcc
	v_lshl_add_u64 v[2:3], v[30:31], 1, s[50:51]
	v_lshl_add_u64 v[2:3], v[2:3], 0, s[28:29]
	v_lshlrev_b32_e32 v0, 1, v74
	v_lshl_add_u64 v[12:13], v[2:3], 0, v[0:1]
	v_mov_b32_e32 v26, v208
	v_mov_b32_e32 v27, v209
	v_mov_b32_e32 v2, v216
	v_mov_b32_e32 v3, v217
	v_mov_b32_e32 v4, v218
	v_mov_b32_e32 v5, v219
	v_mul_f32_e32 v22, v22, v29
	v_cmp_lt_i32_e32 vcc, 7, v28
	s_or_b64 s[6:7], s[6:7], vcc
	v_mul_f32_e32 v2, v2, v22
	v_lshlrev_b32_e32 v22, 16, v26
	v_mul_f32_e32 v2, v2, v22
	v_mul_f32_e32 v22, v23, v29
	v_mul_f32_e32 v3, v3, v22
	v_and_b32_e32 v22, 0xffff0000, v26
	v_mul_f32_e32 v3, v3, v22
	v_cvt_pk_bf16_f32 v2, v2, v3
	v_mul_f32_e32 v3, v24, v29
	v_mul_f32_e32 v3, v4, v3
	v_lshlrev_b32_e32 v4, 16, v27
	v_mul_f32_e32 v3, v3, v4
	v_mul_f32_e32 v4, v25, v29
	v_mul_f32_e32 v4, v5, v4
	v_and_b32_e32 v5, 0xffff0000, v27
	v_mul_f32_e32 v4, v4, v5
	v_cvt_pk_bf16_f32 v3, v3, v4
	s_and_saveexec_b64 s[62:63], s[6:7]
	s_cbranch_execz .LBB0_144
	v_lshl_add_u64 v[4:5], v[10:11], 0, v[0:1]
	global_store_dwordx2 v[4:5], v[2:3], off offset:1024
; __device__ __forceinline__ unsigned cvt_pk_bf16(float lo, float hi) { unsigned r; asm volatile("v_cvt_pk_bf16_f32 %0, %1, %2" : "=v"(r) : "v"(lo), "v"(hi)); return r; }
; __device__ __forceinline__ float bflo(unsigned w) { return __uint_as_float(w << 16); }
; __device__ __forceinline__ float bfhi(unsigned w) { return __uint_as_float(w & 0xffff0000u); }
; __device__ __forceinline__ void retout_unit(CArgs& a, int l, unsigned char* lds, int u, const int tid) {
;     ...
; #pragma unroll
;     for (int et = 0; et < 4; ++et) { const int e0 = 16 * et + 4 * fq;
;         const u32x2 gw = *(const u32x2*)(RG + row * 256 + h * 64 + e0); const f32x4 gg = *(const f32x4*)(a.in[I_RETG] + l * 64 + e0);
;         u32x2 ow; ow.x = cvt_pk_bf16(o[et][0] * ri * gg[0] * bflo(gw.x), o[et][1] * ri * gg[1] * bfhi(gw.x)); ow.y = cvt_pk_bf16(o[et][2] * ri * gg[2] * bflo(gw.y), o[et][3] * ri * gg[3] * bfhi(gw.y));
;         if (!head_rows) *(u32x2*)(OC + row * 1024 + 512 + h * 64 + e0) = ow; }
.LBB0_144:
	s_or_b64 exec, exec, s[62:63]
	v_mov_b32_e32 v2, v220
	v_mov_b32_e32 v3, v221
	v_mov_b32_e32 v4, v222
	v_mov_b32_e32 v5, v223
	v_mov_b32_e32 v22, v210
	v_mov_b32_e32 v23, v211
	v_mul_f32_e32 v18, v18, v29
	v_mul_f32_e32 v19, v19, v29
	v_mul_f32_e32 v20, v20, v29
	v_mul_f32_e32 v21, v21, v29
	v_mul_f32_e32 v2, v18, v2
	v_lshlrev_b32_e32 v18, 16, v22
	v_mul_f32_e32 v3, v19, v3
	v_and_b32_e32 v19, 0xffff0000, v22
	v_mul_f32_e32 v4, v20, v4
	v_lshlrev_b32_e32 v20, 16, v23
	v_mul_f32_e32 v5, v21, v5
	v_and_b32_e32 v21, 0xffff0000, v23
	v_mul_f32_e32 v2, v2, v18
	v_mul_f32_e32 v3, v3, v19
	v_mul_f32_e32 v4, v4, v20
	v_mul_f32_e32 v5, v5, v21
	v_cvt_pk_bf16_f32 v2, v2, v3
	v_cvt_pk_bf16_f32 v3, v4, v5
	s_and_saveexec_b64 s[62:63], s[6:7]
	s_cbranch_execz .LBB0_146
	v_lshl_add_u64 v[4:5], v[10:11], 0, v[0:1]
	global_store_dwordx2 v[4:5], v[2:3], off offset:1056
.LBB0_146:
	s_or_b64 exec, exec, s[62:63]
	v_mov_b32_e32 v2, v224
	v_mov_b32_e32 v3, v225
	v_mov_b32_e32 v4, v226
	v_mov_b32_e32 v5, v227
	v_mov_b32_e32 v18, v212
	v_mov_b32_e32 v19, v213
	v_mul_f32_e32 v14, v14, v29
	v_mul_f32_e32 v15, v15, v29
	v_mul_f32_e32 v16, v16, v29
	v_mul_f32_e32 v17, v17, v29
	v_mul_f32_e32 v2, v14, v2
	v_lshlrev_b32_e32 v14, 16, v18
	v_mul_f32_e32 v3, v15, v3
	v_and_b32_e32 v15, 0xffff0000, v18
	v_mul_f32_e32 v4, v16, v4
	v_lshlrev_b32_e32 v16, 16, v19
	v_mul_f32_e32 v5, v17, v5
	v_and_b32_e32 v17, 0xffff0000, v19
	v_mul_f32_e32 v2, v2, v14
	v_mul_f32_e32 v3, v3, v15
	v_mul_f32_e32 v4, v4, v16
	v_mul_f32_e32 v5, v5, v17
	v_cvt_pk_bf16_f32 v2, v2, v3
	v_cvt_pk_bf16_f32 v3, v4, v5
	s_and_saveexec_b64 s[62:63], s[6:7]
	s_cbranch_execz .LBB0_148
	v_lshl_add_u64 v[4:5], v[10:11], 0, v[0:1]
	global_store_dwordx2 v[4:5], v[2:3], off offset:1088
.LBB0_148:
	s_or_b64 exec, exec, s[62:63]
	v_mov_b32_e32 v2, v228
	v_mov_b32_e32 v3, v229
	v_mov_b32_e32 v4, v230
	v_mov_b32_e32 v5, v231
	v_mov_b32_e32 v12, v214
	v_mov_b32_e32 v13, v215
	v_mul_f32_e32 v8, v8, v29
	v_mul_f32_e32 v9, v9, v29
	v_mul_f32_e32 v6, v6, v29
	v_mul_f32_e32 v7, v7, v29
	v_mul_f32_e32 v2, v8, v2
	v_lshlrev_b32_e32 v8, 16, v12
	v_mul_f32_e32 v3, v9, v3
	v_and_b32_e32 v9, 0xffff0000, v12
	v_mul_f32_e32 v4, v6, v4
	v_lshlrev_b32_e32 v6, 16, v13
	v_mul_f32_e32 v5, v7, v5
	v_and_b32_e32 v7, 0xffff0000, v13
	v_mul_f32_e32 v2, v2, v8
	v_mul_f32_e32 v3, v3, v9
	v_mul_f32_e32 v4, v4, v6
	v_mul_f32_e32 v5, v5, v7
	v_cvt_pk_bf16_f32 v2, v2, v3
	v_cvt_pk_bf16_f32 v3, v4, v5
	s_and_saveexec_b64 s[62:63], s[6:7]
	s_cbranch_execz .LBB0_150
	v_lshl_add_u64 v[4:5], v[10:11], 0, v[0:1]
	global_store_dwordx2 v[4:5], v[2:3], off offset:1120
